# removed all permlane32_swap from both attention loops: P fragments used in MFMA-native key order, V transpose-read addresses remapped to the same key order
# speedup vs baseline: 1.0875x; 1.0238x over previous
; #define SBAR() __builtin_amdgcn_sched_barrier(0)
; #define VRD(D0, L, H) do { constexpr int KS = 2 * 4 * 512, HF = 4 * 512, B0 = (D0) * 512; \
;             L[0] = tr_read<B0>(vb); H[0] = tr_read<B0 + HF>(vb); L[1] = tr_read<B0 + KS>(vb); H[1] = tr_read<B0 + KS + HF>(vb); \
;             L[2] = tr_read<B0 + 2 * KS>(vb); H[2] = tr_read<B0 + 2 * KS + HF>(vb); L[3] = tr_read<B0 + 3 * KS>(vb); H[3] = tr_read<B0 + 3 * KS + HF>(vb); } while (0)
; #define PVM(D0, L, H) do { o[D0] = __builtin_amdgcn_mfma_f32_32x32x16_bf16(fa0, VFR(L, H, 0), o[D0], 0, 0, 0); o[D0] = __builtin_amdgcn_mfma_f32_32x32x16_bf16(fa1, VFR(L, H, 1), o[D0], 0, 0, 0); \
;             o[D0] = __builtin_amdgcn_mfma_f32_32x32x16_bf16(fa2, VFR(L, H, 2), o[D0], 0, 0, 0); o[D0] = __builtin_amdgcn_mfma_f32_32x32x16_bf16(fa3, VFR(L, H, 3), o[D0], 0, 0, 0); } while (0)
; __device__ __forceinline__ void attn_diff1(const bf16* __restrict__ Qrow, const bf16* __restrict__ Kn, const bf16* __restrict__ Vh, const int* __restrict__ posk, const float pq, const float cneg, ...
;     ...
;         const int vb = vb0 + cur;
;     ...
;         s16x4 la[4], ha[4], lb[4], hb[4];
;         VRD(0, la, ha); VRD(1, lb, hb);
;         {   const char* pkl = buf + PK_OFF;
; #pragma unroll
;             for (int i = 0; i < 4; ++i) {
;                 const f32x4 k0 = *(const f32x4*)(pkl + (8 * i + 4 * hi) * 4), k1 = *(const f32x4*)(pkl + (32 + 8 * i + 4 * hi) * 4);
; #pragma unroll
;                 for (int q = 0; q < 4; ++q) { p0[4 * i + q] = fmaf(fabsf(pq - k0[q]), cneg, p0[4 * i + q]); p1[4 * i + q] = fmaf(fabsf(pq - k1[q]), cneg, p1[4 * i + q]); }
;             }
;         }
;         bf16x8 fa0, fa1, fa2, fa3;
;         {   float ps = 0.f;
; #pragma unroll
;             for (int r = 0; r < 16; ++r) { p0[r] = __builtin_amdgcn_exp2f(p0[r]); p1[r] = __builtin_amdgcn_exp2f(p1[r]);     ps += p0[r] + p1[r]; }
;             l_reg += ps; PK4(p0, 0, fa0); PK4(p0, 8, fa1); PK4(p1, 0, fa2); PK4(p1, 8, fa3); }
;         asm volatile("s_waitcnt lgkmcnt(0)" ::: "memory"); SBAR();
;         PVM(0, la, ha); SBAR();
;         VRD(2, la, ha);
;         SBAR(); PVM(1, lb, hb); SBAR();
;         VRD(3, lb, hb);
;         asm volatile("s_waitcnt lgkmcnt(8)" ::: "memory"); SBAR();
;         PVM(2, la, ha);
;         asm volatile("s_waitcnt lgkmcnt(0)" ::: "memory"); SBAR();
;         PVM(3, lb, hb);
.Ld1_skipld:
	v_and_b32_e32 v209, 32, v241
	v_mad_u32_u24 v209, v209, 56, v228
	v_add_u32_e32 v209, s45, v209
	s_waitcnt lgkmcnt(11)
	v_mfma_f32_32x32x16_bf16 v[64:79], v[124:127], v[96:99], 0
	s_waitcnt lgkmcnt(10)
	v_mfma_f32_32x32x16_bf16 v[64:79], v[128:131], v[100:103], v[64:79]
	s_waitcnt lgkmcnt(9)
	v_mfma_f32_32x32x16_bf16 v[64:79], v[132:135], v[112:115], v[64:79]
	s_waitcnt lgkmcnt(8)
	v_mfma_f32_32x32x16_bf16 v[64:79], v[136:139], v[116:119], v[64:79]
	ds_read_b64_tr_b16 v[124:125], v209
	ds_read_b64_tr_b16 v[126:127], v209 offset:256
	ds_read_b64_tr_b16 v[128:129], v209 offset:512
	ds_read_b64_tr_b16 v[130:131], v209 offset:768
	ds_read_b64_tr_b16 v[132:133], v209 offset:1024
	ds_read_b64_tr_b16 v[134:135], v209 offset:1280
	ds_read_b64_tr_b16 v[136:137], v209 offset:1536
	ds_read_b64_tr_b16 v[138:139], v209 offset:1792
	s_waitcnt lgkmcnt(8)
	v_sub_f32_e32 v186, v168, v186
	v_sub_f32_e32 v187, v168, v187
	v_sub_f32_e32 v188, v168, v188
	v_sub_f32_e32 v189, v168, v189
	s_waitcnt lgkmcnt(15)
	v_mfma_f32_32x32x16_bf16 v[80:95], v[140:143], v[96:99], 0
	v_sub_f32_e32 v230, v168, v230
	v_sub_f32_e32 v231, v168, v231
	v_sub_f32_e32 v232, v168, v232
	v_sub_f32_e32 v233, v168, v233
	s_waitcnt lgkmcnt(14)
	v_mfma_f32_32x32x16_bf16 v[80:95], v[144:147], v[100:103], v[80:95]
	v_sub_f32_e32 v234, v168, v234
	v_sub_f32_e32 v235, v168, v235
	v_sub_f32_e32 v236, v168, v236
	v_sub_f32_e32 v237, v168, v237
	s_waitcnt lgkmcnt(13)
	v_mfma_f32_32x32x16_bf16 v[80:95], v[148:151], v[112:115], v[80:95]
	v_sub_f32_e32 v242, v168, v242
	v_sub_f32_e32 v243, v168, v243
	v_sub_f32_e32 v244, v168, v244
	v_sub_f32_e32 v245, v168, v245
	s_waitcnt lgkmcnt(12)
	v_mfma_f32_32x32x16_bf16 v[80:95], v[152:155], v[116:119], v[80:95]
	ds_read_b64_tr_b16 v[140:141], v209 offset:4096
	ds_read_b64_tr_b16 v[142:143], v209 offset:4352
	ds_read_b64_tr_b16 v[144:145], v209 offset:4608
	ds_read_b64_tr_b16 v[146:147], v209 offset:4864
	ds_read_b64_tr_b16 v[148:149], v209 offset:5120
	ds_read_b64_tr_b16 v[150:151], v209 offset:5376
	ds_read_b64_tr_b16 v[152:153], v209 offset:5632
	ds_read_b64_tr_b16 v[154:155], v209 offset:5888
	v_fma_f32 v64, |v186|, -v165, v64
	v_fma_f32 v65, |v187|, -v165, v65
	v_fma_f32 v66, |v188|, -v165, v66
	v_fma_f32 v67, |v189|, -v165, v67
	v_fma_f32 v68, |v230|, -v165, v68
	v_fma_f32 v69, |v231|, -v165, v69
	v_fma_f32 v70, |v232|, -v165, v70
	v_fma_f32 v71, |v233|, -v165, v71
	v_fma_f32 v72, |v234|, -v165, v72
	v_fma_f32 v73, |v235|, -v165, v73
	v_fma_f32 v74, |v236|, -v165, v74
	v_fma_f32 v75, |v237|, -v165, v75
	v_fma_f32 v76, |v242|, -v165, v76
	v_fma_f32 v77, |v243|, -v165, v77
	v_fma_f32 v78, |v244|, -v165, v78
	v_fma_f32 v79, |v245|, -v165, v79
	v_add_u32_e32 v211, s70, v226
	ds_read_b128 v[186:189], v211 offset:30848
	ds_read_b128 v[230:233], v211 offset:30880
	ds_read_b128 v[234:237], v211 offset:30912
	ds_read_b128 v[242:245], v211 offset:30944
	v_exp_f32_e32 v64, v64
	v_exp_f32_e32 v65, v65
	v_add_f32_e32 v184, v184, v64
	v_exp_f32_e32 v66, v66
	v_add_f32_e32 v184, v184, v65
	v_exp_f32_e32 v67, v67
	v_add_f32_e32 v184, v184, v66
	v_exp_f32_e32 v68, v68
	v_add_f32_e32 v184, v184, v67
	v_exp_f32_e32 v69, v69
	v_add_f32_e32 v184, v184, v68
	v_exp_f32_e32 v70, v70
	v_add_f32_e32 v184, v184, v69
	v_exp_f32_e32 v71, v71
	v_add_f32_e32 v184, v184, v70
	v_exp_f32_e32 v72, v72
	v_add_f32_e32 v184, v184, v71
	v_exp_f32_e32 v73, v73
	v_add_f32_e32 v184, v184, v72
	v_exp_f32_e32 v74, v74
	v_add_f32_e32 v184, v184, v73
	v_exp_f32_e32 v75, v75
	v_add_f32_e32 v184, v184, v74
	v_exp_f32_e32 v76, v76
	v_add_f32_e32 v184, v184, v75
	v_exp_f32_e32 v77, v77
	v_add_f32_e32 v184, v184, v76
	v_exp_f32_e32 v78, v78
	v_add_f32_e32 v184, v184, v77
	v_exp_f32_e32 v79, v79
	v_add_f32_e32 v184, v184, v78
	v_add_f32_e32 v184, v184, v79
	v_cvt_pk_bf16_f32 v64, v64, v65
	v_cvt_pk_bf16_f32 v65, v66, v67
	v_cvt_pk_bf16_f32 v66, v68, v69
	v_cvt_pk_bf16_f32 v67, v70, v71
	v_cvt_pk_bf16_f32 v68, v72, v73
	v_cvt_pk_bf16_f32 v69, v74, v75
	v_cvt_pk_bf16_f32 v70, v76, v77
	v_cvt_pk_bf16_f32 v71, v78, v79
	s_nop 1
	s_waitcnt lgkmcnt(15)
	v_mfma_f32_32x32x16_bf16 v[48:63], v[64:67], v[124:127], v[48:63]
	ds_read_b64_tr_b16 v[124:125], v209 offset:8192
	ds_read_b64_tr_b16 v[126:127], v209 offset:8448
	s_waitcnt lgkmcnt(2)
; #define SBAR() __builtin_amdgcn_sched_barrier(0)
; #define SWRITED(boff) do { char* bb_ = lds + (boff); *reinterpret_cast<bf16x8*>(bb_ + KN_OFF + kn_st) = s_kn; *reinterpret_cast<bf16x8*>(bb_ + V_OFF + vst0) = s_v0; \
;     *reinterpret_cast<bf16x8*>(bb_ + V_OFF + vst1) = s_v1; if (tid < 64) *reinterpret_cast<float*>(bb_ + PK_OFF + tid * 4) = s_pk; } while (0)
; #define VRD(D0, L, H) do { constexpr int KS = 2 * 4 * 512, HF = 4 * 512, B0 = (D0) * 512; \
;             L[0] = tr_read<B0>(vb); H[0] = tr_read<B0 + HF>(vb); L[1] = tr_read<B0 + KS>(vb); H[1] = tr_read<B0 + KS + HF>(vb); \
;             L[2] = tr_read<B0 + 2 * KS>(vb); H[2] = tr_read<B0 + 2 * KS + HF>(vb); L[3] = tr_read<B0 + 3 * KS>(vb); H[3] = tr_read<B0 + 3 * KS + HF>(vb); } while (0)
; __device__ __forceinline__ void attn_diff1(const bf16* __restrict__ Qrow, const bf16* __restrict__ Kn, const bf16* __restrict__ Vh, const int* __restrict__ posk, const float pq, const float cneg, ...
;     ...
;         s16x4 la[4], ha[4], lb[4], hb[4];
;         VRD(0, la, ha); VRD(1, lb, hb);
;         {   const char* pkl = buf + PK_OFF;
; #pragma unroll
;             for (int i = 0; i < 4; ++i) {
;                 const f32x4 k0 = *(const f32x4*)(pkl + (8 * i + 4 * hi) * 4), k1 = *(const f32x4*)(pkl + (32 + 8 * i + 4 * hi) * 4);
; #pragma unroll
;                 for (int q = 0; q < 4; ++q) { p0[4 * i + q] = fmaf(fabsf(pq - k0[q]), cneg, p0[4 * i + q]); p1[4 * i + q] = fmaf(fabsf(pq - k1[q]), cneg, p1[4 * i + q]); }
;             }
;         }
;         bf16x8 fa0, fa1, fa2, fa3;
;         {   float ps = 0.f;
; #pragma unroll
;             for (int r = 0; r < 16; ++r) { p0[r] = __builtin_amdgcn_exp2f(p0[r]); p1[r] = __builtin_amdgcn_exp2f(p1[r]);     ps += p0[r] + p1[r]; }
;             l_reg += ps; PK4(p0, 0, fa0); PK4(p0, 8, fa1); PK4(p1, 0, fa2); PK4(p1, 8, fa3); }
;         asm volatile("s_waitcnt lgkmcnt(0)" ::: "memory"); SBAR();
;         PVM(0, la, ha); SBAR();
;         VRD(2, la, ha);
;         SBAR(); PVM(1, lb, hb); SBAR();
;         VRD(3, lb, hb);
;         asm volatile("s_waitcnt lgkmcnt(8)" ::: "memory"); SBAR();
;         PVM(2, la, ha);
;         asm volatile("s_waitcnt lgkmcnt(0)" ::: "memory"); SBAR();
;         PVM(3, lb, hb);
;     ...
;         if (t + 1 < NT) SWRITED(BUF - cur);
	v_sub_f32_e32 v186, v168, v186
	v_sub_f32_e32 v187, v168, v187
	v_sub_f32_e32 v188, v168, v188
	v_sub_f32_e32 v189, v168, v189
	v_sub_f32_e32 v230, v168, v230
	v_sub_f32_e32 v231, v168, v231
	v_sub_f32_e32 v232, v168, v232
	v_sub_f32_e32 v233, v168, v233
	s_waitcnt lgkmcnt(15)
	v_mfma_f32_32x32x16_bf16 v[32:47], v[64:67], v[128:131], v[32:47]
	ds_read_b64_tr_b16 v[128:129], v209 offset:8704
	ds_read_b64_tr_b16 v[130:131], v209 offset:8960
	v_sub_f32_e32 v234, v168, v234
	v_sub_f32_e32 v235, v168, v235
	v_sub_f32_e32 v236, v168, v236
	v_sub_f32_e32 v237, v168, v237
	v_sub_f32_e32 v242, v168, v242
	v_sub_f32_e32 v243, v168, v243
	v_sub_f32_e32 v244, v168, v244
	v_sub_f32_e32 v245, v168, v245
	v_fma_f32 v80, |v186|, -v165, v80
	v_fma_f32 v81, |v187|, -v165, v81
	s_waitcnt lgkmcnt(15)
	v_mfma_f32_32x32x16_bf16 v[16:31], v[64:67], v[132:135], v[16:31]
	ds_read_b64_tr_b16 v[132:133], v209 offset:9216
	ds_read_b64_tr_b16 v[134:135], v209 offset:9472
	v_fma_f32 v82, |v188|, -v165, v82
	v_fma_f32 v83, |v189|, -v165, v83
	v_fma_f32 v84, |v230|, -v165, v84
	v_fma_f32 v85, |v231|, -v165, v85
	v_fma_f32 v86, |v232|, -v165, v86
	v_fma_f32 v87, |v233|, -v165, v87
	v_fma_f32 v88, |v234|, -v165, v88
	v_fma_f32 v89, |v235|, -v165, v89
	v_fma_f32 v90, |v236|, -v165, v90
	v_fma_f32 v91, |v237|, -v165, v91
	s_waitcnt lgkmcnt(15)
	v_mfma_f32_32x32x16_bf16 v[0:15], v[64:67], v[136:139], v[0:15]
	ds_read_b64_tr_b16 v[136:137], v209 offset:9728
	ds_read_b64_tr_b16 v[138:139], v209 offset:9984
	v_fma_f32 v92, |v242|, -v165, v92
	v_fma_f32 v93, |v243|, -v165, v93
	v_fma_f32 v94, |v244|, -v165, v94
	v_fma_f32 v95, |v245|, -v165, v95
	v_exp_f32_e32 v80, v80
	v_exp_f32_e32 v81, v81
	v_add_f32_e32 v184, v184, v80
	v_exp_f32_e32 v82, v82
	v_add_f32_e32 v184, v184, v81
	v_exp_f32_e32 v83, v83
	s_waitcnt lgkmcnt(15)
	v_mfma_f32_32x32x16_bf16 v[48:63], v[68:71], v[140:143], v[48:63]
	ds_read_b64_tr_b16 v[140:141], v209 offset:12288
	ds_read_b64_tr_b16 v[142:143], v209 offset:12544
	v_add_f32_e32 v184, v184, v82
	v_exp_f32_e32 v84, v84
	v_add_f32_e32 v184, v184, v83
	v_exp_f32_e32 v85, v85
	v_add_f32_e32 v184, v184, v84
	v_exp_f32_e32 v86, v86
	v_add_f32_e32 v184, v184, v85
	v_exp_f32_e32 v87, v87
	v_add_f32_e32 v184, v184, v86
	s_waitcnt lgkmcnt(15)
	v_mfma_f32_32x32x16_bf16 v[32:47], v[68:71], v[144:147], v[32:47]
	ds_read_b64_tr_b16 v[144:145], v209 offset:12800
	ds_read_b64_tr_b16 v[146:147], v209 offset:13056
	v_exp_f32_e32 v88, v88
	v_add_f32_e32 v184, v184, v87
	v_exp_f32_e32 v89, v89
	v_add_f32_e32 v184, v184, v88
	v_exp_f32_e32 v90, v90
	v_add_f32_e32 v184, v184, v89
	v_exp_f32_e32 v91, v91
	v_add_f32_e32 v184, v184, v90
	v_exp_f32_e32 v92, v92
	s_waitcnt lgkmcnt(15)
	v_mfma_f32_32x32x16_bf16 v[16:31], v[68:71], v[148:151], v[16:31]
	ds_read_b64_tr_b16 v[148:149], v209 offset:13312
	ds_read_b64_tr_b16 v[150:151], v209 offset:13568
	v_add_f32_e32 v184, v184, v91
	v_exp_f32_e32 v93, v93
	v_add_f32_e32 v184, v184, v92
	v_exp_f32_e32 v94, v94
	v_add_f32_e32 v184, v184, v93
	v_exp_f32_e32 v95, v95
	v_add_f32_e32 v184, v184, v94
	v_add_f32_e32 v184, v184, v95
	v_cvt_pk_bf16_f32 v80, v80, v81
	s_waitcnt lgkmcnt(15)
	v_mfma_f32_32x32x16_bf16 v[0:15], v[68:71], v[152:155], v[0:15]
	ds_read_b64_tr_b16 v[152:153], v209 offset:13824
	ds_read_b64_tr_b16 v[154:155], v209 offset:14080
	v_cvt_pk_bf16_f32 v81, v82, v83
	v_cvt_pk_bf16_f32 v82, v84, v85
	v_cvt_pk_bf16_f32 v83, v86, v87
	v_cvt_pk_bf16_f32 v84, v88, v89
	v_cvt_pk_bf16_f32 v85, v90, v91
	v_cvt_pk_bf16_f32 v86, v92, v93
	v_cvt_pk_bf16_f32 v87, v94, v95
	s_nop 1
	s_waitcnt lgkmcnt(14)
	v_mfma_f32_32x32x16_bf16 v[48:63], v[80:83], v[124:127], v[48:63]
	s_waitcnt lgkmcnt(12)
	v_mfma_f32_32x32x16_bf16 v[32:47], v[80:83], v[128:131], v[32:47]
	s_waitcnt lgkmcnt(10)
	v_mfma_f32_32x32x16_bf16 v[16:31], v[80:83], v[132:135], v[16:31]
	s_waitcnt lgkmcnt(8)
	v_mfma_f32_32x32x16_bf16 v[0:15], v[80:83], v[136:139], v[0:15]
	s_andn2_b64 vcc, exec, s[16:17]
	s_cbranch_vccnz .Ld1_nostage
	s_sub_i32 s70, 0, s45
	v_add_u32_e32 v229, s70, v164
	s_waitcnt vmcnt(0)
	ds_write_b128 v229, v[104:107] offset:30976
	v_add_u32_e32 v229, s70, v219
	ds_write_b128 v229, v[108:111] offset:45312
	v_add_u32_e32 v229, s70, v220
	v_cvt_f32_i32_e32 v207, v207
	ds_write_b128 v229, v[120:123] offset:45312
	s_and_saveexec_b64 s[16:17], s[42:43]
	s_cbranch_execz .Ld1_stg_done
	v_add_u32_e32 v229, s70, v227
	ds_write_b32 v229, v207 offset:61696

; #define SBAR() __builtin_amdgcn_sched_barrier(0)
; #define SLOAD2(k0) do { s_kn = *reinterpret_cast<const bf16x8*>(Kn + (size_t)((k0) + kn_r) * 1024 + kn_c); s_kr = *reinterpret_cast<const bf16x8*>(Kr + (size_t)((k0) + kr_r) * 32 + kr_c); \
;     s_v = *reinterpret_cast<const bf16x8*>(Vh + (size_t)((k0) + kn_r) * 1024 + kn_c); } while (0)
; __device__ __forceinline__ void attn_mla2(const bf16* __restrict__ Q0, const bf16* __restrict__ Q1, const bf16* __restrict__ Kn, const bf16* __restrict__ Kr, const bf16* __restrict__ Vh, ...
;     ...
;     for (int t = 0; t < NT; ++t) {
;         const char* buf = lds + cur;
;         f32x16 pa0 = f32x16{}, pa1 = f32x16{}, pb0 = f32x16{}, pb1 = f32x16{};
;         {
;             const char* kb = buf + KN_OFF + r32 * 144 + hi * 16; const char* kr = buf + KR_OFF + r32 * 80 + hi * 16;
;     ...
;             bf16x8 c0 = KLD0(0), c1 = KLD1(0);
; #pragma unroll
;             for (int d0 = 0; d0 < 6; ++d0) {
;                 bf16x8 n0 = c0, n1 = c1;
;                 if (d0 + 1 < 6) { n0 = KLD0(d0 + 1); n1 = KLD1(d0 + 1); }
;                 pa0 = __builtin_amdgcn_mfma_f32_32x32x16_bf16(c0, q0[d0], pa0, 0, 0, 0); pb0 = __builtin_amdgcn_mfma_f32_32x32x16_bf16(c0, q1[d0], pb0, 0, 0, 0);
;                 pa1 = __builtin_amdgcn_mfma_f32_32x32x16_bf16(c1, q0[d0], pa1, 0, 0, 0); pb1 = __builtin_amdgcn_mfma_f32_32x32x16_bf16(c1, q1[d0], pb1, 0, 0, 0);
;                 SBAR(); c0 = n0; c1 = n1;
;             }
;     ...
;         }
;         if (t + 1 < NT) SLOAD2((t + 1) * 64);
;         bf16x8 fa0, fa1, fa2, fa3, fb0, fb1, fb2, fb3;
;         {   float ps = 0.f;
; #pragma unroll
;             for (int r = 0; r < 16; ++r) { pa0[r] = __builtin_amdgcn_exp2f(pa0[r]); pa1[r] = __builtin_amdgcn_exp2f(pa1[r]);     ps += pa0[r] + pa1[r]; }
;             l0 += ps; PK4(pa0, 0, fa0); PK4(pa0, 8, fa1); PK4(pa1, 0, fa2); PK4(pa1, 8, fa3); }
;         {   float ps = 0.f;
; #pragma unroll
;             for (int r = 0; r < 16; ++r) { pb0[r] = __builtin_amdgcn_exp2f(pb0[r]); pb1[r] = __builtin_amdgcn_exp2f(pb1[r]); ps += pb0[r] + pb1[r]; }
;             l1 += ps; PK4(pb0, 0, fb0); PK4(pb0, 8, fb1); PK4(pb1, 0, fb2); PK4(pb1, 8, fb3); }
.LBB0_1629:
	s_add_i32 s12, s16, 0
	v_add3_u32 v184, s12, v246, v244
	v_add3_u32 v188, s12, v245, v244
	ds_read_b128 v[196:199], v184
	ds_read_b128 v[200:203], v184 offset:32
	ds_read_b128 v[204:207], v184 offset:64
	ds_read_b128 v[208:211], v184 offset:96
	ds_read_b128 v[212:215], v188 offset:9216
	ds_read_b128 v[216:219], v188 offset:9248
	ds_read_b128 v[220:223], v184 offset:4608
	ds_read_b128 v[224:227], v184 offset:4640
	ds_read_b128 v[228:231], v184 offset:4672
	ds_read_b128 v[232:235], v184 offset:4704
	ds_read_b128 v[236:239], v188 offset:11776
	ds_read_b128 v[250:253], v188 offset:11808
	v_lshl_add_u64 v[176:177], v[194:195], 0, s[2:3]
	s_mov_b32 s12, 0x8e20000
	v_add_co_u32_e32 v178, vcc, s12, v176
	s_mov_b32 s12, 0xae20000
	s_nop 0
	v_addc_co_u32_e32 v179, vcc, 0, v177, vcc
	v_add_co_u32_e32 v176, vcc, s12, v176
	s_nop 1
	v_addc_co_u32_e32 v177, vcc, 0, v177, vcc
	global_load_dwordx4 v[180:183], v[178:179], off
	global_load_dwordx4 v[176:179], v[176:177], off
	v_lshl_add_u64 v[186:187], v[192:193], 0, s[2:3]
	global_load_dwordx2 v[186:187], v[186:187], off
	s_waitcnt lgkmcnt(11)
	v_mfma_f32_32x32x16_bf16 v[96:111], v[196:199], v[160:163], 0
	s_sub_i32 s15, 0, s16
	v_ashrrev_i32_e32 v80, 3, v241
	v_and_b32_e32 v81, 7, v241
	s_waitcnt lgkmcnt(10)
	v_mfma_f32_32x32x16_bf16 v[96:111], v[200:203], v[168:171], v[96:111]
	v_lshlrev_b32_e32 v82, 4, v81
	v_mul_u32_u24_e32 v184, 0x90, v80
	v_add3_u32 v184, s15, v184, v82
	s_waitcnt lgkmcnt(9)
	v_mfma_f32_32x32x16_bf16 v[96:111], v[204:207], v[156:159], v[96:111]
	v_mul_u32_u24_e32 v189, 0x50, v80
	v_lshlrev_b32_e32 v83, 3, v81
	v_add3_u32 v189, s15, v189, v83
	s_waitcnt lgkmcnt(8)
	v_mfma_f32_32x32x16_bf16 v[96:111], v[208:211], v[144:147], v[96:111]
	v_bfe_u32 v83, v241, 3, 2
	v_and_b32_e32 v82, 48, v82
	v_lshlrev_b32_e32 v84, 1, v80
	s_waitcnt lgkmcnt(7)
	v_mfma_f32_32x32x16_bf16 v[96:111], v[212:215], v[140:143], v[96:111]
	v_and_b32_e32 v85, 0x1fffff0, v80
	v_and_b32_e32 v84, 8, v84
	v_or3_b32 v81, v84, v85, v81
	s_waitcnt lgkmcnt(6)
	v_mfma_f32_32x32x16_bf16 v[96:111], v[216:219], v[128:131], v[96:111]
	v_lshrrev_b32_e32 v80, 1, v80
	v_lshlrev_b32_e32 v81, 7, v81
	v_and_b32_e32 v81, 0xfffffe00, v81
	v_and_or_b32 v83, v80, 4, v83
	v_lshlrev_b32_e32 v83, 6, v83
	v_mfma_f32_32x32x16_bf16 v[64:79], v[196:199], v[164:167], 0
	v_add_u32_e32 v80, s15, v81
	v_add3_u32 v188, v80, v83, v82
	v_lshl_add_u64 v[192:193], v[192:193], 0, s[30:31]
	v_lshl_add_u64 v[194:195], v[194:195], 0, s[36:37]
	s_nop 0
	v_mfma_f32_32x32x16_bf16 v[64:79], v[200:203], v[172:175], v[64:79]
	v_exp_f32_e32 v96, v96
	v_exp_f32_e32 v97, v97
	v_add_f32_e32 v190, v190, v96
	v_exp_f32_e32 v98, v98
	v_add_f32_e32 v190, v190, v97
	v_mfma_f32_32x32x16_bf16 v[64:79], v[204:207], v[152:155], v[64:79]
	v_exp_f32_e32 v99, v99
	v_add_f32_e32 v190, v190, v98
	v_exp_f32_e32 v100, v100
	v_add_f32_e32 v190, v190, v99
	v_exp_f32_e32 v101, v101
	v_mfma_f32_32x32x16_bf16 v[64:79], v[208:211], v[148:151], v[64:79]
	v_add_f32_e32 v190, v190, v100
	v_exp_f32_e32 v102, v102
	v_add_f32_e32 v190, v190, v101
	v_exp_f32_e32 v103, v103
	v_add_f32_e32 v190, v190, v102
	v_exp_f32_e32 v104, v104
	v_mfma_f32_32x32x16_bf16 v[64:79], v[212:215], v[136:139], v[64:79]
	v_add_f32_e32 v190, v190, v103
	v_exp_f32_e32 v105, v105
	v_add_f32_e32 v190, v190, v104
	v_exp_f32_e32 v106, v106
	v_add_f32_e32 v190, v190, v105
	v_mfma_f32_32x32x16_bf16 v[64:79], v[216:219], v[132:135], v[64:79]
	v_exp_f32_e32 v107, v107
	v_add_f32_e32 v190, v190, v106
	v_exp_f32_e32 v108, v108
	v_add_f32_e32 v190, v190, v107
	v_exp_f32_e32 v109, v109
	v_and_b32_e32 v213, 32, v241
	v_mad_u32_u24 v212, v213, 24, v248
	v_add_u32_e32 v212, s16, v212
	s_waitcnt lgkmcnt(5)
	v_mfma_f32_32x32x16_bf16 v[112:127], v[220:223], v[160:163], 0
	v_add_f32_e32 v190, v190, v108
	v_exp_f32_e32 v110, v110
	v_add_f32_e32 v190, v190, v109
	v_exp_f32_e32 v111, v111
	v_add_f32_e32 v190, v190, v110
	v_add_f32_e32 v190, v190, v111
	s_waitcnt lgkmcnt(4)
	v_mfma_f32_32x32x16_bf16 v[112:127], v[224:227], v[168:171], v[112:127]
	v_exp_f32_e32 v64, v64
	v_exp_f32_e32 v65, v65
	v_add_f32_e32 v191, v191, v64
	v_exp_f32_e32 v66, v66
	v_add_f32_e32 v191, v191, v65
	s_waitcnt lgkmcnt(3)
	v_mfma_f32_32x32x16_bf16 v[112:127], v[228:231], v[156:159], v[112:127]
	v_exp_f32_e32 v67, v67
	v_add_f32_e32 v191, v191, v66
	v_exp_f32_e32 v68, v68
	v_add_f32_e32 v191, v191, v67
	v_exp_f32_e32 v69, v69
	s_waitcnt lgkmcnt(2)
	v_mfma_f32_32x32x16_bf16 v[112:127], v[232:235], v[144:147], v[112:127]
	v_add_f32_e32 v191, v191, v68
	v_exp_f32_e32 v70, v70
	v_add_f32_e32 v191, v191, v69
	v_exp_f32_e32 v71, v71
	v_add_f32_e32 v191, v191, v70
	v_exp_f32_e32 v72, v72
	s_waitcnt lgkmcnt(1)
	v_mfma_f32_32x32x16_bf16 v[112:127], v[236:239], v[140:143], v[112:127]
	v_add_f32_e32 v191, v191, v71
	v_exp_f32_e32 v73, v73
	v_add_f32_e32 v191, v191, v72
	v_exp_f32_e32 v74, v74
	v_add_f32_e32 v191, v191, v73
	s_waitcnt lgkmcnt(0)
; template <int DVB> __device__ __forceinline__ int v_st(int k, int c) { const int kk = (k & ~0xC) | ((k & 4) << 1) | ((k & 8) >> 1); return ((kk >> 3) * DVB + (c >> 5)) * 512 + ((kk & 7) * 32 + (c & 31)) * 2; }
; __device__ __forceinline__ void attn_mla2(const bf16* __restrict__ Q0, const bf16* __restrict__ Q1, const bf16* __restrict__ Kn, const bf16* __restrict__ Kr, const bf16* __restrict__ Vh, ...
;     ...
;         {   float ps = 0.f;
; #pragma unroll
;             for (int r = 0; r < 16; ++r) { pa0[r] = __builtin_amdgcn_exp2f(pa0[r]); pa1[r] = __builtin_amdgcn_exp2f(pa1[r]);     ps += pa0[r] + pa1[r]; }
;             l0 += ps; PK4(pa0, 0, fa0); PK4(pa0, 8, fa1); PK4(pa1, 0, fa2); PK4(pa1, 8, fa3); }
;         {   float ps = 0.f;
; #pragma unroll
;             for (int r = 0; r < 16; ++r) { pb0[r] = __builtin_amdgcn_exp2f(pb0[r]); pb1[r] = __builtin_amdgcn_exp2f(pb1[r]); ps += pb0[r] + pb1[r]; }
;             l1 += ps; PK4(pb0, 0, fb0); PK4(pb0, 8, fb1); PK4(pb1, 0, fb2); PK4(pb1, 8, fb3); }
;         {   const int vb = vb0 + cur;
;     ...
;             PV2(0); PV2(1);
;     ...
;         }
;         if (t + 1 < NT) {
;             int tw = tid; asm volatile("" : "+v"(tw));
;             char* bb_ = lds + (BUF - cur);
;             *reinterpret_cast<bf16x8*>(bb_ + KN_OFF + (tw >> 3) * 144 + (tw & 7) * 16) = s_kn;
;             if (tw < 256) *reinterpret_cast<bf16x8*>(bb_ + KR_OFF + ((tw >> 2) & 63) * 80 + (tw & 3) * 16) = s_kr;
;             *reinterpret_cast<bf16x8*>(bb_ + V_OFF + v_st<2>(tw >> 3, (tw & 7) * 8)) = s_v;
;         }
;         __syncthreads();
;         cur = BUF - cur;
	v_mfma_f32_32x32x16_bf16 v[112:127], v[250:253], v[128:131], v[112:127]
	v_exp_f32_e32 v75, v75
	v_add_f32_e32 v191, v191, v74
	v_exp_f32_e32 v76, v76
	v_add_f32_e32 v191, v191, v75
	v_exp_f32_e32 v77, v77
	v_mfma_f32_32x32x16_bf16 v[80:95], v[220:223], v[164:167], 0
	v_add_f32_e32 v191, v191, v76
	v_exp_f32_e32 v78, v78
	v_add_f32_e32 v191, v191, v77
	v_exp_f32_e32 v79, v79
	v_add_f32_e32 v191, v191, v78
	v_add_f32_e32 v191, v191, v79
	v_mfma_f32_32x32x16_bf16 v[80:95], v[224:227], v[172:175], v[80:95]
	v_cvt_pk_bf16_f32 v196, v96, v97
	v_cvt_pk_bf16_f32 v197, v98, v99
	v_cvt_pk_bf16_f32 v198, v100, v101
	v_cvt_pk_bf16_f32 v199, v102, v103
	v_cvt_pk_bf16_f32 v200, v104, v105
	v_cvt_pk_bf16_f32 v201, v106, v107
	v_cvt_pk_bf16_f32 v202, v108, v109
	v_cvt_pk_bf16_f32 v203, v110, v111
	v_mfma_f32_32x32x16_bf16 v[80:95], v[228:231], v[152:155], v[80:95]
	ds_read_b64_tr_b16 v[96:97], v212 offset:0
	ds_read_b64_tr_b16 v[98:99], v212 offset:256
	ds_read_b64_tr_b16 v[100:101], v212 offset:2048
	ds_read_b64_tr_b16 v[102:103], v212 offset:2304
	ds_read_b64_tr_b16 v[104:105], v212 offset:512
	ds_read_b64_tr_b16 v[106:107], v212 offset:768
	ds_read_b64_tr_b16 v[108:109], v212 offset:2560
	ds_read_b64_tr_b16 v[110:111], v212 offset:2816
	v_mfma_f32_32x32x16_bf16 v[80:95], v[232:235], v[148:151], v[80:95]
	v_cvt_pk_bf16_f32 v204, v64, v65
	v_cvt_pk_bf16_f32 v205, v66, v67
	v_cvt_pk_bf16_f32 v206, v68, v69
	v_cvt_pk_bf16_f32 v207, v70, v71
	v_cvt_pk_bf16_f32 v208, v72, v73
	v_cvt_pk_bf16_f32 v209, v74, v75
	v_cvt_pk_bf16_f32 v210, v76, v77
	v_cvt_pk_bf16_f32 v211, v78, v79
	v_mfma_f32_32x32x16_bf16 v[80:95], v[236:239], v[136:139], v[80:95]
	ds_read_b64_tr_b16 v[64:65], v212 offset:4096
	ds_read_b64_tr_b16 v[66:67], v212 offset:4352
	ds_read_b64_tr_b16 v[68:69], v212 offset:6144
	ds_read_b64_tr_b16 v[70:71], v212 offset:6400
	ds_read_b64_tr_b16 v[72:73], v212 offset:4608
	ds_read_b64_tr_b16 v[74:75], v212 offset:4864
	ds_read_b64_tr_b16 v[76:77], v212 offset:6656
	ds_read_b64_tr_b16 v[78:79], v212 offset:6912
	v_mfma_f32_32x32x16_bf16 v[80:95], v[250:253], v[132:135], v[80:95]
	v_exp_f32_e32 v112, v112
	v_exp_f32_e32 v113, v113
	v_add_f32_e32 v190, v190, v112
	v_exp_f32_e32 v114, v114
	v_add_f32_e32 v190, v190, v113
	s_waitcnt lgkmcnt(8)
	v_mfma_f32_32x32x16_bf16 v[0:15], v[196:199], v[96:99], v[0:15]
	v_exp_f32_e32 v115, v115
	v_add_f32_e32 v190, v190, v114
	v_exp_f32_e32 v116, v116
	v_add_f32_e32 v190, v190, v115
	v_exp_f32_e32 v117, v117
	v_mfma_f32_32x32x16_bf16 v[32:47], v[204:207], v[96:99], v[32:47]
	v_add_f32_e32 v190, v190, v116
	v_exp_f32_e32 v118, v118
	v_add_f32_e32 v190, v190, v117
	v_exp_f32_e32 v119, v119
	v_add_f32_e32 v190, v190, v118
	v_exp_f32_e32 v120, v120
	v_mfma_f32_32x32x16_bf16 v[16:31], v[196:199], v[104:107], v[16:31]
	v_add_f32_e32 v190, v190, v119
	v_exp_f32_e32 v121, v121
	v_add_f32_e32 v190, v190, v120
	v_exp_f32_e32 v122, v122
	v_add_f32_e32 v190, v190, v121
	v_mfma_f32_32x32x16_bf16 v[48:63], v[204:207], v[104:107], v[48:63]
	v_exp_f32_e32 v123, v123
	v_add_f32_e32 v190, v190, v122
	v_exp_f32_e32 v124, v124
	v_add_f32_e32 v190, v190, v123
	v_exp_f32_e32 v125, v125
	v_mfma_f32_32x32x16_bf16 v[0:15], v[200:203], v[100:103], v[0:15]
	v_add_f32_e32 v190, v190, v124
	v_exp_f32_e32 v126, v126
	v_add_f32_e32 v190, v190, v125
	v_exp_f32_e32 v127, v127
	v_add_f32_e32 v190, v190, v126
	v_add_f32_e32 v190, v190, v127
	v_mfma_f32_32x32x16_bf16 v[32:47], v[208:211], v[100:103], v[32:47]
	v_cvt_pk_bf16_f32 v220, v112, v113
	v_cvt_pk_bf16_f32 v221, v114, v115
	v_cvt_pk_bf16_f32 v222, v116, v117
	v_cvt_pk_bf16_f32 v223, v118, v119
	v_cvt_pk_bf16_f32 v224, v120, v121
	v_cvt_pk_bf16_f32 v225, v122, v123
	v_cvt_pk_bf16_f32 v226, v124, v125
	v_cvt_pk_bf16_f32 v227, v126, v127
	v_mfma_f32_32x32x16_bf16 v[16:31], v[200:203], v[108:111], v[16:31]
	v_exp_f32_e32 v80, v80
	v_exp_f32_e32 v81, v81
	v_add_f32_e32 v191, v191, v80
	v_exp_f32_e32 v82, v82
	v_mfma_f32_32x32x16_bf16 v[48:63], v[208:211], v[108:111], v[48:63]
	v_add_f32_e32 v191, v191, v81
	v_exp_f32_e32 v83, v83
	v_add_f32_e32 v191, v191, v82
	v_exp_f32_e32 v84, v84
	v_add_f32_e32 v191, v191, v83
	s_waitcnt lgkmcnt(0)
	v_mfma_f32_32x32x16_bf16 v[0:15], v[220:223], v[64:67], v[0:15]
	v_exp_f32_e32 v85, v85
	v_add_f32_e32 v191, v191, v84
	v_exp_f32_e32 v86, v86
	v_add_f32_e32 v191, v191, v85
	v_exp_f32_e32 v87, v87
	v_add_f32_e32 v191, v191, v86
	v_mfma_f32_32x32x16_bf16 v[16:31], v[220:223], v[72:75], v[16:31]
	v_exp_f32_e32 v88, v88
	v_add_f32_e32 v191, v191, v87
	v_exp_f32_e32 v89, v89
	v_add_f32_e32 v191, v191, v88
	v_exp_f32_e32 v90, v90
	v_mfma_f32_32x32x16_bf16 v[0:15], v[224:227], v[68:71], v[0:15]
	v_add_f32_e32 v191, v191, v89
	v_exp_f32_e32 v91, v91
	v_add_f32_e32 v191, v191, v90
	v_exp_f32_e32 v92, v92
	v_add_f32_e32 v191, v191, v91
	v_exp_f32_e32 v93, v93
	v_mfma_f32_32x32x16_bf16 v[16:31], v[224:227], v[76:79], v[16:31]
	v_add_f32_e32 v191, v191, v92
	v_exp_f32_e32 v94, v94
	v_add_f32_e32 v191, v191, v93
	v_exp_f32_e32 v95, v95
	v_add_f32_e32 v191, v191, v94
	v_add_f32_e32 v191, v191, v95
	v_cvt_pk_bf16_f32 v228, v80, v81
	v_cvt_pk_bf16_f32 v229, v82, v83
	v_cvt_pk_bf16_f32 v230, v84, v85
	v_cvt_pk_bf16_f32 v231, v86, v87
	v_cvt_pk_bf16_f32 v232, v88, v89
	v_cvt_pk_bf16_f32 v233, v90, v91
	v_cvt_pk_bf16_f32 v234, v92, v93
	v_cvt_pk_bf16_f32 v235, v94, v95
	s_waitcnt vmcnt(0)
	ds_write_b128 v184, v[180:183] offset:30976
	ds_write_b128 v188, v[176:179] offset:45312
	ds_write_b64 v189, v[186:187] offset:40192
	s_sub_i32 s16, 0x7900, s16
	s_add_i32 s14, s14, -1
	s_cmp_eq_u32 s14, 0
	v_mfma_f32_32x32x16_bf16 v[32:47], v[228:231], v[64:67], v[32:47]
	v_mfma_f32_32x32x16_bf16 v[48:63], v[228:231], v[72:75], v[48:63]
	v_mfma_f32_32x32x16_bf16 v[32:47], v[232:235], v[68:71], v[32:47]
	v_mfma_f32_32x32x16_bf16 v[48:63], v[232:235], v[76:79], v[48:63]
	s_waitcnt lgkmcnt(0)
	s_barrier
	s_cbranch_scc1 .LBB0_1633
	v_mov_b32_e32 v240, 0x358637bd
	s_branch .LBB0_1629
